# retention epilogue: all 16 gate/groupnorm loads issued up front (was a two-ahead load-wait ladder across 8 groups), plain-op group math, dwordx4 stores via permlane32_swap
# speedup vs baseline: 1.0032x; 1.0032x over previous
.LBB0_1187:
	v_lshlrev_b32_e32 v130, 1, v114
	v_lshl_add_u64 v[32:33], v[112:113], 0, v[130:131]
	v_readlane_b32 s8, v253, 40
	v_readlane_b32 s9, v253, 41
	s_lshl_b32 s0, s19, 2
	s_add_u32 s4, s8, s0
	s_addc_u32 s5, s9, 0
	v_lshlrev_b32_e32 v44, 2, v114
	s_nop 0
	global_load_dwordx2 v[182:183], v[32:33], off offset:3072
	global_load_dwordx2 v[184:185], v[32:33], off offset:3088
	global_load_dwordx2 v[186:187], v[32:33], off offset:3104
	global_load_dwordx2 v[188:189], v[32:33], off offset:3120
	global_load_dwordx2 v[190:191], v[32:33], off offset:3136
	global_load_dwordx2 v[192:193], v[32:33], off offset:3152
	global_load_dwordx2 v[194:195], v[32:33], off offset:3168
	global_load_dwordx2 v[196:197], v[32:33], off offset:3184
	global_load_dwordx4 v[198:201], v44, s[4:5]
	global_load_dwordx4 v[202:205], v44, s[4:5] offset:32
	global_load_dwordx4 v[206:209], v44, s[4:5] offset:64
	global_load_dwordx4 v[210:213], v44, s[4:5] offset:96
	global_load_dwordx4 v[214:217], v44, s[4:5] offset:128
	global_load_dwordx4 v[218:221], v44, s[4:5] offset:160
	global_load_dwordx4 v[222:225], v44, s[4:5] offset:192
	global_load_dwordx4 v[226:229], v44, s[4:5] offset:224
	s_nop 7
	v_add_f32_e32 v45, v16, v0
	v_add_f32_e32 v46, v17, v1
	v_add_f32_e32 v45, 0, v45
	v_add_f32_e32 v47, v18, v2
	v_add_f32_e32 v45, v46, v45
	v_add_f32_e32 v48, v19, v3
	v_add_f32_e32 v45, v47, v45
	v_add_f32_e32 v49, v20, v4
	v_add_f32_e32 v45, v48, v45
	v_add_f32_e32 v52, v21, v5
	v_add_f32_e32 v45, v49, v45
	v_pk_add_f32 v[34:35], v[22:23], v[6:7]
	v_add_f32_e32 v45, v52, v45
	v_add_f32_e32 v34, v34, v45
	v_pk_add_f32 v[36:37], v[24:25], v[8:9]
	v_add_f32_e32 v34, v35, v34
	v_add_f32_e32 v34, v36, v34
	v_pk_add_f32 v[38:39], v[26:27], v[10:11]
	v_add_f32_e32 v34, v37, v34
	v_add_f32_e32 v34, v38, v34
	v_pk_add_f32 v[40:41], v[28:29], v[12:13]
	v_add_f32_e32 v34, v39, v34
	v_add_f32_e32 v34, v40, v34
	v_readlane_b32 s4, v253, 36
	s_lshl_b32 s0, s19, 2
	v_pk_add_f32 v[42:43], v[30:31], v[14:15]
	v_add_f32_e32 v34, v41, v34
	v_readlane_b32 s8, v253, 40
	v_add_f32_e32 v34, v42, v34
	v_readlane_b32 s5, v253, 37
	v_readlane_b32 s9, v253, 41
	s_add_u32 s4, s8, s0
	v_lshlrev_b32_e32 v44, 2, v114
	v_add_f32_e32 v34, v43, v34
	s_addc_u32 s5, s9, 0
	v_cmp_lt_i32_e32 vcc, v163, v133
	s_mov_b32 s0, 0x800000
	v_readlane_b32 s6, v253, 38
	v_cndmask_b32_e32 v53, v129, v163, vcc
	v_lshlrev_b32_e32 v64, 2, v53
	ds_bpermute_b32 v35, v64, v34
	v_readlane_b32 s7, v253, 39
	v_readlane_b32 s10, v253, 42
	v_readlane_b32 s11, v253, 43
	s_waitcnt lgkmcnt(0)
	v_add_f32_e32 v34, v34, v35
	v_mul_f32_e32 v52, 0x3c800000, v34
	v_pk_add_f32 v[16:17], v[16:17], v[52:53] op_sel_hi:[1,0] neg_lo:[0,1] neg_hi:[0,1]
	v_pk_add_f32 v[36:37], v[10:11], v[52:53] op_sel_hi:[1,0] neg_lo:[0,1] neg_hi:[0,1]
	v_pk_add_f32 v[26:27], v[26:27], v[52:53] op_sel_hi:[1,0] neg_lo:[0,1] neg_hi:[0,1]
	v_pk_add_f32 v[34:35], v[12:13], v[52:53] op_sel_hi:[1,0] neg_lo:[0,1] neg_hi:[0,1]
	v_pk_add_f32 v[12:13], v[28:29], v[52:53] op_sel_hi:[1,0] neg_lo:[0,1] neg_hi:[0,1]
	v_pk_add_f32 v[28:29], v[14:15], v[52:53] op_sel_hi:[1,0] neg_lo:[0,1] neg_hi:[0,1]
	v_pk_add_f32 v[10:11], v[30:31], v[52:53] op_sel_hi:[1,0] neg_lo:[0,1] neg_hi:[0,1]
	v_pk_add_f32 v[2:3], v[2:3], v[52:53] op_sel_hi:[1,0] neg_lo:[0,1] neg_hi:[0,1]
	v_pk_add_f32 v[0:1], v[0:1], v[52:53] op_sel_hi:[1,0] neg_lo:[0,1] neg_hi:[0,1]
	v_pk_add_f32 v[38:39], v[6:7], v[52:53] op_sel_hi:[1,0] neg_lo:[0,1] neg_hi:[0,1]
	v_pk_add_f32 v[40:41], v[4:5], v[52:53] op_sel_hi:[1,0] neg_lo:[0,1] neg_hi:[0,1]
	v_pk_add_f32 v[30:31], v[8:9], v[52:53] op_sel_hi:[1,0] neg_lo:[0,1] neg_hi:[0,1]
	v_pk_add_f32 v[18:19], v[18:19], v[52:53] op_sel_hi:[1,0] neg_lo:[0,1] neg_hi:[0,1]
	v_pk_add_f32 v[8:9], v[22:23], v[52:53] op_sel_hi:[1,0] neg_lo:[0,1] neg_hi:[0,1]
	v_pk_add_f32 v[14:15], v[20:21], v[52:53] op_sel_hi:[1,0] neg_lo:[0,1] neg_hi:[0,1]
	v_pk_add_f32 v[4:5], v[24:25], v[52:53] op_sel_hi:[1,0] neg_lo:[0,1] neg_hi:[0,1]
	v_mul_f32_e32 v230, v0, v0
	v_mul_f32_e32 v231, v1, v1
	v_mul_f32_e32 v232, v2, v2
	v_mul_f32_e32 v233, v3, v3
	v_fmac_f32_e32 v230, v40, v40
	v_fmac_f32_e32 v231, v41, v41
	v_fmac_f32_e32 v232, v38, v38
	v_fmac_f32_e32 v233, v39, v39
	v_fmac_f32_e32 v230, v30, v30
	v_fmac_f32_e32 v231, v31, v31
	v_fmac_f32_e32 v232, v36, v36
	v_fmac_f32_e32 v233, v37, v37
	v_fmac_f32_e32 v230, v34, v34
	v_fmac_f32_e32 v231, v35, v35
	v_fmac_f32_e32 v232, v28, v28
	v_fmac_f32_e32 v233, v29, v29
	v_fmac_f32_e32 v230, v16, v16
	v_fmac_f32_e32 v231, v17, v17
	v_fmac_f32_e32 v232, v18, v18
	v_fmac_f32_e32 v233, v19, v19
	v_fmac_f32_e32 v230, v14, v14
	v_fmac_f32_e32 v231, v15, v15
	v_fmac_f32_e32 v232, v8, v8
	v_fmac_f32_e32 v233, v9, v9
	v_fmac_f32_e32 v230, v4, v4
	v_fmac_f32_e32 v231, v5, v5
	v_fmac_f32_e32 v232, v26, v26
	v_fmac_f32_e32 v233, v27, v27
	v_fmac_f32_e32 v230, v12, v12
	v_fmac_f32_e32 v231, v13, v13
	v_fmac_f32_e32 v232, v10, v10
	v_fmac_f32_e32 v233, v11, v11
	v_add_f32_e32 v230, v230, v231
	v_add_f32_e32 v232, v232, v233
	v_add_f32_e32 v230, v230, v232
	v_mov_b32_e32 v231, v230
	s_nop 1
	v_permlane32_swap_b32_e32 v230, v231
	v_add_f32_e32 v230, v230, v231
	v_mov_b32_e32 v231, 0x3727c5ac
	v_fmamk_f32 v230, v230, 0x3c800000, v231
	v_rsq_f32_e32 v230, v230
	v_lshl_add_u64 v[246:247], v[32:33], 0, v[130:131]
	s_waitcnt vmcnt(0)
	v_lshlrev_b32_e32 v232, 16, v182
	v_and_b32_e32 v233, 0xffff0000, v182
	v_lshlrev_b32_e32 v234, 16, v183
	v_and_b32_e32 v235, 0xffff0000, v183
	v_mul_f32_e32 v236, 0xbfb8aa3b, v232
	v_mul_f32_e32 v237, 0xbfb8aa3b, v233
	v_mul_f32_e32 v238, 0xbfb8aa3b, v234
	v_mul_f32_e32 v239, 0xbfb8aa3b, v235
	v_exp_f32_e32 v236, v236
	v_exp_f32_e32 v237, v237
	v_exp_f32_e32 v238, v238
	v_exp_f32_e32 v239, v239
	v_mul_f32_e32 v0, v0, v230
	v_mul_f32_e32 v1, v1, v230
	v_mul_f32_e32 v2, v2, v230
	v_mul_f32_e32 v3, v3, v230
	v_add_f32_e32 v236, 1.0, v236
	v_add_f32_e32 v237, 1.0, v237
	v_add_f32_e32 v238, 1.0, v238
	v_add_f32_e32 v239, 1.0, v239
	v_rcp_f32_e32 v236, v236
	v_rcp_f32_e32 v237, v237
	v_rcp_f32_e32 v238, v238
	v_rcp_f32_e32 v239, v239
	v_mul_f32_e32 v0, v0, v198
	v_mul_f32_e32 v1, v1, v199
	v_mul_f32_e32 v2, v2, v200
	v_mul_f32_e32 v3, v3, v201
	v_mul_f32_e32 v232, v232, v236
	v_mul_f32_e32 v233, v233, v237
	v_mul_f32_e32 v234, v234, v238
	v_mul_f32_e32 v235, v235, v239
	v_mul_f32_e32 v0, v0, v232
	v_mul_f32_e32 v1, v1, v233
	v_mul_f32_e32 v2, v2, v234
	v_mul_f32_e32 v3, v3, v235
	v_cvt_pk_bf16_f32 v182, v0, v1
	v_cvt_pk_bf16_f32 v183, v2, v3
	v_lshlrev_b32_e32 v232, 16, v184
	v_and_b32_e32 v233, 0xffff0000, v184
	v_lshlrev_b32_e32 v234, 16, v185
	v_and_b32_e32 v235, 0xffff0000, v185
	v_mul_f32_e32 v236, 0xbfb8aa3b, v232
	v_mul_f32_e32 v237, 0xbfb8aa3b, v233
	v_mul_f32_e32 v238, 0xbfb8aa3b, v234
	v_mul_f32_e32 v239, 0xbfb8aa3b, v235
	v_exp_f32_e32 v236, v236
	v_exp_f32_e32 v237, v237
	v_exp_f32_e32 v238, v238
	v_exp_f32_e32 v239, v239
	v_mul_f32_e32 v40, v40, v230
	v_mul_f32_e32 v41, v41, v230
	v_mul_f32_e32 v38, v38, v230
	v_mul_f32_e32 v39, v39, v230
	v_add_f32_e32 v236, 1.0, v236
	v_add_f32_e32 v237, 1.0, v237
	v_add_f32_e32 v238, 1.0, v238
	v_add_f32_e32 v239, 1.0, v239
	v_rcp_f32_e32 v236, v236
	v_rcp_f32_e32 v237, v237
	v_rcp_f32_e32 v238, v238
	v_rcp_f32_e32 v239, v239
	v_mul_f32_e32 v40, v40, v202
	v_mul_f32_e32 v41, v41, v203
	v_mul_f32_e32 v38, v38, v204
	v_mul_f32_e32 v39, v39, v205
	v_mul_f32_e32 v232, v232, v236
	v_mul_f32_e32 v233, v233, v237
	v_mul_f32_e32 v234, v234, v238
	v_mul_f32_e32 v235, v235, v239
	v_mul_f32_e32 v40, v40, v232
	v_mul_f32_e32 v41, v41, v233
	v_mul_f32_e32 v38, v38, v234
	v_mul_f32_e32 v39, v39, v235
	v_cvt_pk_bf16_f32 v184, v40, v41
	v_cvt_pk_bf16_f32 v185, v38, v39
	s_nop 1
	v_permlane32_swap_b32_e32 v182, v184
	v_permlane32_swap_b32_e32 v183, v185
	global_store_dwordx4 v[246:247], v[182:185], off offset:3072
	v_lshlrev_b32_e32 v232, 16, v186
	v_and_b32_e32 v233, 0xffff0000, v186
	v_lshlrev_b32_e32 v234, 16, v187
	v_and_b32_e32 v235, 0xffff0000, v187
	v_mul_f32_e32 v236, 0xbfb8aa3b, v232
	v_mul_f32_e32 v237, 0xbfb8aa3b, v233
	v_mul_f32_e32 v238, 0xbfb8aa3b, v234
	v_mul_f32_e32 v239, 0xbfb8aa3b, v235
	v_exp_f32_e32 v236, v236
	v_exp_f32_e32 v237, v237
	v_exp_f32_e32 v238, v238
	v_exp_f32_e32 v239, v239
	v_mul_f32_e32 v30, v30, v230
	v_mul_f32_e32 v31, v31, v230
	v_mul_f32_e32 v36, v36, v230
	v_mul_f32_e32 v37, v37, v230
	v_add_f32_e32 v236, 1.0, v236
	v_add_f32_e32 v237, 1.0, v237
	v_add_f32_e32 v238, 1.0, v238
	v_add_f32_e32 v239, 1.0, v239
	v_rcp_f32_e32 v236, v236
	v_rcp_f32_e32 v237, v237
	v_rcp_f32_e32 v238, v238
	v_rcp_f32_e32 v239, v239
	v_mul_f32_e32 v30, v30, v206
	v_mul_f32_e32 v31, v31, v207
	v_mul_f32_e32 v36, v36, v208
	v_mul_f32_e32 v37, v37, v209
	v_mul_f32_e32 v232, v232, v236
	v_mul_f32_e32 v233, v233, v237
	v_mul_f32_e32 v234, v234, v238
	v_mul_f32_e32 v235, v235, v239
	v_mul_f32_e32 v30, v30, v232
	v_mul_f32_e32 v31, v31, v233
	v_mul_f32_e32 v36, v36, v234
	v_mul_f32_e32 v37, v37, v235
	v_cvt_pk_bf16_f32 v186, v30, v31
	v_cvt_pk_bf16_f32 v187, v36, v37
	v_lshlrev_b32_e32 v232, 16, v188
	v_and_b32_e32 v233, 0xffff0000, v188
	v_lshlrev_b32_e32 v234, 16, v189
	v_and_b32_e32 v235, 0xffff0000, v189
	v_mul_f32_e32 v236, 0xbfb8aa3b, v232
	v_mul_f32_e32 v237, 0xbfb8aa3b, v233
	v_mul_f32_e32 v238, 0xbfb8aa3b, v234
	v_mul_f32_e32 v239, 0xbfb8aa3b, v235
	v_exp_f32_e32 v236, v236
	v_exp_f32_e32 v237, v237
	v_exp_f32_e32 v238, v238
	v_exp_f32_e32 v239, v239
	v_mul_f32_e32 v34, v34, v230
	v_mul_f32_e32 v35, v35, v230
	v_mul_f32_e32 v28, v28, v230
	v_mul_f32_e32 v29, v29, v230
	v_add_f32_e32 v236, 1.0, v236
	v_add_f32_e32 v237, 1.0, v237
	v_add_f32_e32 v238, 1.0, v238
	v_add_f32_e32 v239, 1.0, v239
	v_rcp_f32_e32 v236, v236
	v_rcp_f32_e32 v237, v237
	v_rcp_f32_e32 v238, v238
	v_rcp_f32_e32 v239, v239
	v_mul_f32_e32 v34, v34, v210
	v_mul_f32_e32 v35, v35, v211
	v_mul_f32_e32 v28, v28, v212
	v_mul_f32_e32 v29, v29, v213
	v_mul_f32_e32 v232, v232, v236
	v_mul_f32_e32 v233, v233, v237
	v_mul_f32_e32 v234, v234, v238
	v_mul_f32_e32 v235, v235, v239
	v_mul_f32_e32 v34, v34, v232
	v_mul_f32_e32 v35, v35, v233
	v_mul_f32_e32 v28, v28, v234
	v_mul_f32_e32 v29, v29, v235
	v_cvt_pk_bf16_f32 v188, v34, v35
	v_cvt_pk_bf16_f32 v189, v28, v29
	s_nop 1
	v_permlane32_swap_b32_e32 v186, v188
	v_permlane32_swap_b32_e32 v187, v189
	global_store_dwordx4 v[246:247], v[186:189], off offset:3104
	v_lshlrev_b32_e32 v232, 16, v190
	v_and_b32_e32 v233, 0xffff0000, v190
	v_lshlrev_b32_e32 v234, 16, v191
	v_and_b32_e32 v235, 0xffff0000, v191
	v_mul_f32_e32 v236, 0xbfb8aa3b, v232
	v_mul_f32_e32 v237, 0xbfb8aa3b, v233
	v_mul_f32_e32 v238, 0xbfb8aa3b, v234
	v_mul_f32_e32 v239, 0xbfb8aa3b, v235
	v_exp_f32_e32 v236, v236
	v_exp_f32_e32 v237, v237
	v_exp_f32_e32 v238, v238
	v_exp_f32_e32 v239, v239
	v_mul_f32_e32 v16, v16, v230
	v_mul_f32_e32 v17, v17, v230
	v_mul_f32_e32 v18, v18, v230
	v_mul_f32_e32 v19, v19, v230
	v_add_f32_e32 v236, 1.0, v236
	v_add_f32_e32 v237, 1.0, v237
	v_add_f32_e32 v238, 1.0, v238
	v_add_f32_e32 v239, 1.0, v239
	v_rcp_f32_e32 v236, v236
	v_rcp_f32_e32 v237, v237
	v_rcp_f32_e32 v238, v238
	v_rcp_f32_e32 v239, v239
	v_mul_f32_e32 v16, v16, v214
	v_mul_f32_e32 v17, v17, v215
	v_mul_f32_e32 v18, v18, v216
	v_mul_f32_e32 v19, v19, v217
	v_mul_f32_e32 v232, v232, v236
	v_mul_f32_e32 v233, v233, v237
	v_mul_f32_e32 v234, v234, v238
	v_mul_f32_e32 v235, v235, v239
	v_mul_f32_e32 v16, v16, v232
	v_mul_f32_e32 v17, v17, v233
	v_mul_f32_e32 v18, v18, v234
	v_mul_f32_e32 v19, v19, v235
	v_cvt_pk_bf16_f32 v190, v16, v17
	v_cvt_pk_bf16_f32 v191, v18, v19
	v_lshlrev_b32_e32 v232, 16, v192
	v_and_b32_e32 v233, 0xffff0000, v192
	v_lshlrev_b32_e32 v234, 16, v193
	v_and_b32_e32 v235, 0xffff0000, v193
	v_mul_f32_e32 v236, 0xbfb8aa3b, v232
	v_mul_f32_e32 v237, 0xbfb8aa3b, v233
	v_mul_f32_e32 v238, 0xbfb8aa3b, v234
	v_mul_f32_e32 v239, 0xbfb8aa3b, v235
	v_exp_f32_e32 v236, v236
	v_exp_f32_e32 v237, v237
	v_exp_f32_e32 v238, v238
	v_exp_f32_e32 v239, v239
	v_mul_f32_e32 v14, v14, v230
	v_mul_f32_e32 v15, v15, v230
	v_mul_f32_e32 v8, v8, v230
	v_mul_f32_e32 v9, v9, v230
	v_add_f32_e32 v236, 1.0, v236
	v_add_f32_e32 v237, 1.0, v237
	v_add_f32_e32 v238, 1.0, v238
	v_add_f32_e32 v239, 1.0, v239
	v_rcp_f32_e32 v236, v236
	v_rcp_f32_e32 v237, v237
	v_rcp_f32_e32 v238, v238
	v_rcp_f32_e32 v239, v239
	v_mul_f32_e32 v14, v14, v218
	v_mul_f32_e32 v15, v15, v219
	v_mul_f32_e32 v8, v8, v220
	v_mul_f32_e32 v9, v9, v221
	v_mul_f32_e32 v232, v232, v236
	v_mul_f32_e32 v233, v233, v237
	v_mul_f32_e32 v234, v234, v238
	v_mul_f32_e32 v235, v235, v239
	v_mul_f32_e32 v14, v14, v232
	v_mul_f32_e32 v15, v15, v233
	v_mul_f32_e32 v8, v8, v234
	v_mul_f32_e32 v9, v9, v235
	v_cvt_pk_bf16_f32 v192, v14, v15
	v_cvt_pk_bf16_f32 v193, v8, v9
	s_nop 1
	v_permlane32_swap_b32_e32 v190, v192
	v_permlane32_swap_b32_e32 v191, v193
	global_store_dwordx4 v[246:247], v[190:193], off offset:3136
	v_lshlrev_b32_e32 v232, 16, v194
	v_and_b32_e32 v233, 0xffff0000, v194
	v_lshlrev_b32_e32 v234, 16, v195
	v_and_b32_e32 v235, 0xffff0000, v195
	v_mul_f32_e32 v236, 0xbfb8aa3b, v232
	v_mul_f32_e32 v237, 0xbfb8aa3b, v233
	v_mul_f32_e32 v238, 0xbfb8aa3b, v234
	v_mul_f32_e32 v239, 0xbfb8aa3b, v235
	v_exp_f32_e32 v236, v236
	v_exp_f32_e32 v237, v237
	v_exp_f32_e32 v238, v238
	v_exp_f32_e32 v239, v239
	v_mul_f32_e32 v4, v4, v230
	v_mul_f32_e32 v5, v5, v230
	v_mul_f32_e32 v26, v26, v230
	v_mul_f32_e32 v27, v27, v230
	v_add_f32_e32 v236, 1.0, v236
	v_add_f32_e32 v237, 1.0, v237
	v_add_f32_e32 v238, 1.0, v238
	v_add_f32_e32 v239, 1.0, v239
	v_rcp_f32_e32 v236, v236
	v_rcp_f32_e32 v237, v237
	v_rcp_f32_e32 v238, v238
	v_rcp_f32_e32 v239, v239
	v_mul_f32_e32 v4, v4, v222
	v_mul_f32_e32 v5, v5, v223
	v_mul_f32_e32 v26, v26, v224
	v_mul_f32_e32 v27, v27, v225
	v_mul_f32_e32 v232, v232, v236
	v_mul_f32_e32 v233, v233, v237
	v_mul_f32_e32 v234, v234, v238
	v_mul_f32_e32 v235, v235, v239
	v_mul_f32_e32 v4, v4, v232
	v_mul_f32_e32 v5, v5, v233
	v_mul_f32_e32 v26, v26, v234
	v_mul_f32_e32 v27, v27, v235
	v_cvt_pk_bf16_f32 v194, v4, v5
	v_cvt_pk_bf16_f32 v195, v26, v27
	v_lshlrev_b32_e32 v232, 16, v196
	v_and_b32_e32 v233, 0xffff0000, v196
	v_lshlrev_b32_e32 v234, 16, v197
	v_and_b32_e32 v235, 0xffff0000, v197
	v_mul_f32_e32 v236, 0xbfb8aa3b, v232
	v_mul_f32_e32 v237, 0xbfb8aa3b, v233
	v_mul_f32_e32 v238, 0xbfb8aa3b, v234
	v_mul_f32_e32 v239, 0xbfb8aa3b, v235
	v_exp_f32_e32 v236, v236
	v_exp_f32_e32 v237, v237
	v_exp_f32_e32 v238, v238
	v_exp_f32_e32 v239, v239
	v_mul_f32_e32 v12, v12, v230
	v_mul_f32_e32 v13, v13, v230
	v_mul_f32_e32 v10, v10, v230
	v_mul_f32_e32 v11, v11, v230
	v_add_f32_e32 v236, 1.0, v236
	v_add_f32_e32 v237, 1.0, v237
	v_add_f32_e32 v238, 1.0, v238
	v_add_f32_e32 v239, 1.0, v239
	v_rcp_f32_e32 v236, v236
	v_rcp_f32_e32 v237, v237
	v_rcp_f32_e32 v238, v238
	v_rcp_f32_e32 v239, v239
	v_mul_f32_e32 v12, v12, v226
	v_mul_f32_e32 v13, v13, v227
	v_mul_f32_e32 v10, v10, v228
	v_mul_f32_e32 v11, v11, v229
	v_mul_f32_e32 v232, v232, v236
	v_mul_f32_e32 v233, v233, v237
	v_mul_f32_e32 v234, v234, v238
	v_mul_f32_e32 v235, v235, v239
	v_mul_f32_e32 v12, v12, v232
	v_mul_f32_e32 v13, v13, v233
	v_mul_f32_e32 v10, v10, v234
	v_mul_f32_e32 v11, v11, v235
	v_cvt_pk_bf16_f32 v196, v12, v13
	v_cvt_pk_bf16_f32 v197, v10, v11
	s_nop 1
	v_permlane32_swap_b32_e32 v194, v196
	v_permlane32_swap_b32_e32 v195, v197
	global_store_dwordx4 v[246:247], v[194:197], off offset:3168
	s_mov_b64 s[4:5], 0
